# dense attention: static priority 3 instead of 1 for waves 4-7 (strategy 4 variant)
# baseline (speedup 1.0000x reference)
; __device__ __forceinline__ void sincos_fast(float ang, float& sn, float& cs) { const float f = __builtin_amdgcn_fractf(ang * 0.15915494309189535f); sn = __builtin_amdgcn_sinf(f); cs = __builtin_amdgcn_cosf(f); }
; template <int MODE, int QMODE> ...
;     ...
;   const int wid = __builtin_amdgcn_readfirstlane(tid >> 6), lane = tid & 63, r32 = lane & 31, hi = lane >> 5;
;   const int wrow = MODE ? (wid & 3) * QBLK : wid * QBLK, wcol = MODE ? (wid >> 2) * D : 0;
;   bf16* V_lds = (bf16*)lds; bf16* K_lds = (bf16*)(lds + 2 * SHM_V);
;   float* ws = (float*)(lds + 2 * SHM_V + 2 * SHM_K) + wid * 64; float* li_l = ws; float* al_l = ws + 32;
;   float m_reg = MODE ? sinkp[wid >> 2] * (1.0f / SCALE) : -1e30f, l_reg = MODE ? 1.f : 0.f; bf16x8 qr[8];
;   const bf16* Qw = Qb + (long)(wrow + r32) * LDQ + wcol + hi * 8;
; #pragma unroll
;   for (int d0 = 0; d0 < 8; ++d0) qr[d0] = __builtin_nontemporal_load((const bf16x8*)(Qw + d0 * 16));
;   if constexpr (QMODE != 0) {
;     const int t = t0 + wrow + r32; constexpr float L2T = 13.287712379549449f;
;     if constexpr (QMODE == 2) {
;       float ssq = 0.f;
; #pragma unroll
;       for (int d0 = 0; d0 < 8; ++d0)
; #pragma unroll
;         for (int j = 0; j < 8; ++j) { const float x = bf2f(qr[d0][j]); ssq += x * x; }
;       { auto rr = __builtin_amdgcn_permlane32_swap(__float_as_uint(ssq), __float_as_uint(ssq), false, false); ssq = __uint_as_float(rr[0]) + __uint_as_float(rr[1]); }
;       const float rn = 1.0f / sqrtf(ssq * (1.0f / 128.0f) + 1e-6f);
;       const float posr = (float)(t >> 6), posc = (float)(t & 63);
;     ...
;           for (int j = 0; j < 8; ++j) { const int i = dd * 16 + hi * 8 + j; const float inv = __builtin_amdgcn_exp2f(-(float)i * (L2T / 32.0f));
;             float sn, cs; sincos_fast((hf ? posc : posr) * inv, sn, cs);
.LBB0_168:
	s_mul_i32 s3, s8, 0x1800
	s_mul_hi_u32 s2, s8, 0x1800
	s_add_u32 s3, s40, s3
	s_addc_u32 s16, s41, s2
	s_lshl_b32 s47, s48, 7
	s_lshl_b32 s2, s48, 8
	s_add_u32 s2, s3, s2
	v_mov_b32_e32 v229, v0
	s_addc_u32 s3, s16, 0
	s_waitcnt vmcnt(28)
	v_mov_b64_e32 v[2:3], s[2:3]
	v_readfirstlane_b32 s16, v229
	s_ashr_i32 s18, s16, 6
	v_and_b32_e32 v233, 31, v229
	s_lshl_b32 s46, s18, 5
	v_bfe_u32 v226, v229, 5, 1
	v_or_b32_e32 v4, s46, v233
	v_mad_i64_i32 v[2:3], s[2:3], v4, s56, v[2:3]
	v_lshlrev_b32_e32 v210, 4, v226
	s_waitcnt vmcnt(0)
	v_lshl_add_u64 v[30:31], v[2:3], 0, v[210:211]
	global_load_dwordx4 v[10:13], v[30:31], off offset:3232 nt
	global_load_dwordx4 v[14:17], v[30:31], off offset:3296 nt
	v_and_b32_e32 v37, 32, v229
	global_load_dwordx4 v[64:67], v37, s[54:55]
	global_load_dwordx4 v[70:73], v37, s[54:55] offset:16
	global_load_dwordx4 v[6:9], v37, s[54:55] offset:128
	global_load_dwordx4 v[2:5], v37, s[54:55] offset:144
	global_load_dwordx4 v[78:81], v[30:31], off offset:3136 nt
	global_load_dwordx4 v[86:89], v[30:31], off offset:3072 nt
	v_lshlrev_b32_e32 v98, 3, v226
	s_sub_i32 s2, s8, s17
	v_cvt_f32_ubyte0_e32 v18, v98
	v_or_b32_e32 v19, 1, v98
	v_or_b32_e32 v20, 2, v98
	v_or_b32_e32 v21, 3, v98
	v_or_b32_e32 v22, 4, v98
	v_or_b32_e32 v23, 5, v98
	v_mul_f32_e32 v18, 0xbed49a78, v18
	v_cvt_f32_ubyte0_e32 v19, v19
	v_cvt_f32_ubyte0_e32 v20, v20
	v_cvt_f32_ubyte0_e32 v21, v21
	v_cvt_f32_ubyte0_e32 v22, v22
	s_add_i32 s2, s46, s2
	v_cvt_f32_ubyte0_e32 v23, v23
	v_exp_f32_e32 v102, v18
	v_mul_f32_e32 v18, 0xbed49a78, v19
	v_mul_f32_e32 v19, 0xbed49a78, v20
	v_mul_f32_e32 v20, 0xbed49a78, v21
	v_mul_f32_e32 v21, 0xbed49a78, v22
	v_add_u32_e32 v22, s2, v233
	v_mul_f32_e32 v42, 0xbed49a78, v23
	v_exp_f32_e32 v103, v18
	v_exp_f32_e32 v110, v19
	v_exp_f32_e32 v111, v20
	v_exp_f32_e32 v126, v21
	v_ashrrev_i32_e32 v26, 6, v22
	v_and_b32_e32 v34, 63, v22
	global_load_dwordx4 v[18:21], v[30:31], off offset:3200 nt
	global_load_dwordx4 v[22:25], v[30:31], off offset:3264 nt
	v_cvt_f32_i32_e32 v99, v26
	global_load_dwordx4 v[26:29], v[30:31], off offset:3104 nt
	s_nop 0
	global_load_dwordx4 v[30:33], v[30:31], off offset:3168 nt
	v_cvt_f32_ubyte0_e32 v35, v34
	v_or_b32_e32 v46, 6, v98
	v_mul_f32_e32 v34, v102, v99
	v_mul_f32_e32 v36, v103, v99
	v_mul_f32_e32 v34, 0.15915494, v34
	v_mul_f32_e32 v36, 0.15915494, v36
	v_fract_f32_e32 v34, v34
	v_fract_f32_e32 v36, v36
	v_mul_f32_e32 v38, v110, v99
	s_waitcnt lgkmcnt(0)
	v_mul_f32_e32 v39, v111, v99
	v_sin_f32_e32 v52, v34
	v_cos_f32_e32 v53, v34
	v_sin_f32_e32 v49, v36
	v_cos_f32_e32 v48, v36
	v_mul_f32_e32 v40, v126, v99
	v_mul_f32_e32 v38, 0.15915494, v38
	v_mul_f32_e32 v39, 0.15915494, v39
	v_cvt_f32_ubyte0_e32 v46, v46
	v_mul_f32_e32 v43, 0.15915494, v40
	v_fract_f32_e32 v38, v38
	v_fract_f32_e32 v39, v39
	v_mul_f32_e32 v46, 0xbed49a78, v46
	v_sin_f32_e32 v44, v38
	v_cos_f32_e32 v45, v38
	v_sin_f32_e32 v41, v39
	v_cos_f32_e32 v40, v39
	v_exp_f32_e32 v127, v46
	v_or_b32_e32 v57, 17, v98
	v_cvt_f32_ubyte0_e32 v57, v57
	v_mul_f32_e32 v57, 0xbed49a78, v57
	v_exp_f32_e32 v167, v57
	v_mov_b32_e32 v124, v53
	v_mov_b32_e32 v125, v52
	v_mov_b32_e32 v122, v49
	v_mov_b32_e32 v123, v48
	v_mov_b32_e32 v120, v45
	v_mov_b32_e32 v121, v44
	v_mov_b32_e32 v116, v41
	v_mov_b32_e32 v117, v40
	s_waitcnt vmcnt(9)
	v_mov_b32_e32 v108, v64
	v_mul_f32_e32 v64, v167, v99
	v_lshlrev_b32_e32 v36, 16, v13
	v_and_b32_e32 v34, 0xffff0000, v13
	v_exp_f32_e32 v13, v42
	v_and_b32_e32 v39, 0xffff0000, v17
	v_lshlrev_b32_e32 v38, 16, v17
	v_fract_f32_e32 v17, v43
	v_sin_f32_e32 v42, v17
	v_cos_f32_e32 v43, v17
	v_mul_f32_e32 v17, v13, v99
	v_mul_f32_e32 v17, 0.15915494, v17
	v_fract_f32_e32 v17, v17
	v_sin_f32_e32 v51, v17
	v_cos_f32_e32 v50, v17
	v_mul_f32_e32 v17, v127, v99
	v_mul_f32_e32 v17, 0.15915494, v17
	v_fract_f32_e32 v17, v17
	v_sin_f32_e32 v46, v17
	v_cos_f32_e32 v47, v17
	v_or_b32_e32 v17, 7, v98
	v_cvt_f32_ubyte0_e32 v17, v17
	v_mul_f32_e32 v17, 0xbed49a78, v17
	v_exp_f32_e32 v17, v17
	s_waitcnt vmcnt(6)
	v_mov_b32_e32 v61, v4
	v_mul_f32_e32 v13, v13, v35
	v_mul_f32_e32 v13, 0.15915494, v13
	v_mul_f32_e32 v4, v17, v99
	v_mul_f32_e32 v4, 0.15915494, v4
	v_fract_f32_e32 v4, v4
	v_sin_f32_e32 v59, v4
	v_cos_f32_e32 v58, v4
	v_or_b32_e32 v4, 16, v98
	v_fract_f32_e32 v13, v13
	s_waitcnt vmcnt(5)
	v_lshlrev_b32_e32 v93, 16, v79
	v_and_b32_e32 v95, 0xffff0000, v79
	v_lshlrev_b32_e32 v101, 16, v78
	v_and_b32_e32 v107, 0xffff0000, v78
	v_cvt_f32_ubyte0_e32 v4, v4
	v_sin_f32_e32 v79, v13
	v_cos_f32_e32 v78, v13
	v_mul_f32_e32 v13, v127, v35
	v_mul_f32_e32 v4, 0xbed49a78, v4
	v_mul_f32_e32 v13, 0.15915494, v13
	v_mov_b32_e32 v77, v2
	v_mov_b32_e32 v2, v71
	v_exp_f32_e32 v166, v4
	v_or_b32_e32 v71, 20, v98
	v_fract_f32_e32 v13, v13
	v_lshlrev_b32_e32 v55, 16, v81
	v_and_b32_e32 v63, 0xffff0000, v81
	v_lshlrev_b32_e32 v69, 16, v80
	v_and_b32_e32 v75, 0xffff0000, v80
	v_cvt_f32_ubyte0_e32 v71, v71
	v_sin_f32_e32 v80, v13
	v_cos_f32_e32 v81, v13
	v_mul_f32_e32 v13, v17, v35
	v_mul_f32_e32 v71, 0xbed49a78, v71
	v_mul_f32_e32 v13, 0.15915494, v13
	v_exp_f32_e32 v250, v71
	v_fract_f32_e32 v13, v13
	s_waitcnt vmcnt(4)
	v_lshlrev_b32_e32 v92, 16, v87
	v_and_b32_e32 v94, 0xffff0000, v87
	v_lshlrev_b32_e32 v100, 16, v86
	v_and_b32_e32 v106, 0xffff0000, v86
	v_sin_f32_e32 v87, v13
	v_cos_f32_e32 v86, v13
	v_mul_f32_e32 v13, v166, v35
	v_mul_f32_e32 v13, 0.15915494, v13
	v_fract_f32_e32 v13, v13
	s_waitcnt vmcnt(3)
; __device__ __forceinline__ void sincos_fast(float ang, float& sn, float& cs) { const float f = __builtin_amdgcn_fractf(ang * 0.15915494309189535f); sn = __builtin_amdgcn_sinf(f); cs = __builtin_amdgcn_cosf(f); }
; template <int MODE, int QMODE> ...
;     ...
;       float ssq = 0.f;
; #pragma unroll
;       for (int d0 = 0; d0 < 8; ++d0)
; #pragma unroll
;         for (int j = 0; j < 8; ++j) { const float x = bf2f(qr[d0][j]); ssq += x * x; }
;       { auto rr = __builtin_amdgcn_permlane32_swap(__float_as_uint(ssq), __float_as_uint(ssq), false, false); ssq = __uint_as_float(rr[0]) + __uint_as_float(rr[1]); }
;       const float rn = 1.0f / sqrtf(ssq * (1.0f / 128.0f) + 1e-6f);
;     ...
;           for (int j = 0; j < 8; ++j) { const int i = dd * 16 + hi * 8 + j; const float inv = __builtin_amdgcn_exp2f(-(float)i * (L2T / 32.0f));
;             float sn, cs; sincos_fast((hf ? posc : posr) * inv, sn, cs);
	v_lshlrev_b32_e32 v184, 16, v19
	v_and_b32_e32 v182, 0xffff0000, v19
	v_lshlrev_b32_e32 v198, 16, v18
	v_and_b32_e32 v196, 0xffff0000, v18
	v_sin_f32_e32 v18, v13
	v_cos_f32_e32 v19, v13
	v_mul_f32_e32 v13, v167, v35
	v_lshlrev_b32_e32 v177, 16, v14
	v_and_b32_e32 v167, 0xffff0000, v14
	v_mul_f32_e32 v14, v250, v35
	v_pk_mul_f32 v[200:201], v[100:101], v[100:101]
	v_pk_mul_f32 v[202:203], v[106:107], v[106:107]
	v_mul_f32_e32 v14, 0.15915494, v14
	v_pk_mul_f32 v[186:187], v[92:93], v[92:93]
	s_waitcnt vmcnt(0)
	v_lshlrev_b32_e32 v181, 16, v32
	v_lshlrev_b32_e32 v180, 16, v28
	v_and_b32_e32 v179, 0xffff0000, v32
	v_and_b32_e32 v178, 0xffff0000, v28
	v_mul_f32_e32 v28, v103, v35
	v_mul_f32_e32 v32, v111, v35
	v_lshlrev_b32_e32 v103, 16, v25
	v_and_b32_e32 v111, 0xffff0000, v25
	v_lshlrev_b32_e32 v127, 16, v15
	v_and_b32_e32 v25, 0xffff0000, v15
	v_fract_f32_e32 v15, v14
	v_add_f32_e32 v14, v200, v202
	v_lshlrev_b32_e32 v68, 16, v88
	v_pk_mul_f32 v[192:193], v[94:95], v[94:95]
	v_add_f32_e32 v14, v186, v14
	v_pk_mul_f32 v[134:135], v[68:69], v[68:69]
	v_and_b32_e32 v74, 0xffff0000, v88
	v_add_f32_e32 v14, v192, v14
	v_lshlrev_b32_e32 v54, 16, v89
	v_pk_mul_f32 v[136:137], v[74:75], v[74:75]
	v_add_f32_e32 v14, v134, v14
	v_pk_mul_f32 v[130:131], v[54:55], v[54:55]
	v_and_b32_e32 v62, 0xffff0000, v89
	v_add_f32_e32 v14, v136, v14
	v_pk_mul_f32 v[132:133], v[62:63], v[62:63]
	v_lshlrev_b32_e32 v207, 16, v30
	v_lshlrev_b32_e32 v206, 16, v26
	v_add_f32_e32 v14, v130, v14
	v_pk_mul_f32 v[222:223], v[206:207], v[206:207]
	v_and_b32_e32 v205, 0xffff0000, v30
	v_and_b32_e32 v204, 0xffff0000, v26
	v_add_f32_e32 v14, v132, v14
	v_lshlrev_b32_e32 v191, 16, v31
	v_lshlrev_b32_e32 v190, 16, v27
	v_pk_mul_f32 v[230:231], v[204:205], v[204:205]
	v_add_f32_e32 v14, v222, v14
	v_pk_mul_f32 v[218:219], v[190:191], v[190:191]
	v_and_b32_e32 v189, 0xffff0000, v31
	v_and_b32_e32 v188, 0xffff0000, v27
	v_add_f32_e32 v14, v230, v14
	v_pk_mul_f32 v[220:221], v[188:189], v[188:189]
	v_add_f32_e32 v14, v218, v14
	v_pk_mul_f32 v[214:215], v[180:181], v[180:181]
	v_add_f32_e32 v14, v220, v14
	v_lshlrev_b32_e32 v141, 16, v33
	v_lshlrev_b32_e32 v140, 16, v29
	v_pk_mul_f32 v[216:217], v[178:179], v[178:179]
	v_add_f32_e32 v14, v214, v14
	v_pk_mul_f32 v[208:209], v[140:141], v[140:141]
	v_and_b32_e32 v139, 0xffff0000, v33
	v_and_b32_e32 v138, 0xffff0000, v29
	v_add_f32_e32 v14, v216, v14
	v_pk_mul_f32 v[212:213], v[138:139], v[138:139]
	v_add_f32_e32 v14, v208, v14
	v_add_f32_e32 v14, v212, v14
	v_add_f32_e32 v130, v201, v14
	v_mov_b32_e32 v4, v73
	v_or_b32_e32 v73, 21, v98
	v_add_f32_e32 v130, v203, v130
	v_cvt_f32_ubyte0_e32 v73, v73
	v_add_f32_e32 v130, v187, v130
	v_mul_f32_e32 v73, 0xbed49a78, v73
	v_add_f32_e32 v130, v193, v130
	v_exp_f32_e32 v251, v73
	v_or_b32_e32 v73, 22, v98
	v_add_f32_e32 v130, v135, v130
	v_mov_b32_e32 v60, v72
	v_mul_f32_e32 v72, v250, v99
	v_cvt_f32_ubyte0_e32 v73, v73
	v_add_f32_e32 v130, v137, v130
	v_mul_f32_e32 v72, 0.15915494, v72
	v_mul_f32_e32 v73, 0xbed49a78, v73
	v_add_f32_e32 v132, v131, v130
	v_fract_f32_e32 v72, v72
	v_exp_f32_e32 v228, v73
	v_add_f32_e32 v132, v133, v132
	v_sin_f32_e32 v82, v72
	v_cos_f32_e32 v83, v72
	v_mul_f32_e32 v72, v251, v99
	v_add_f32_e32 v132, v223, v132
	v_mul_f32_e32 v72, 0.15915494, v72
	v_add_f32_e32 v132, v231, v132
	v_fract_f32_e32 v72, v72
	v_add_f32_e32 v132, v219, v132
	v_sin_f32_e32 v89, v72
	v_cos_f32_e32 v88, v72
	v_mul_f32_e32 v72, v228, v99
	v_add_f32_e32 v132, v221, v132
	v_mul_f32_e32 v72, 0.15915494, v72
	v_add_f32_e32 v132, v215, v132
	v_fract_f32_e32 v72, v72
	v_add_f32_e32 v132, v217, v132
	v_sin_f32_e32 v90, v72
	v_cos_f32_e32 v91, v72
	v_or_b32_e32 v72, 23, v98
	v_lshlrev_b32_e32 v199, 16, v22
	v_add_f32_e32 v132, v209, v132
	v_mov_b32_e32 v109, v6
	v_mov_b32_e32 v6, v65
	v_or_b32_e32 v65, 18, v98
	v_cvt_f32_ubyte0_e32 v72, v72
	v_pk_mul_f32 v[246:247], v[198:199], v[198:199]
	v_and_b32_e32 v197, 0xffff0000, v22
	v_add_f32_e32 v132, v213, v132
	v_cvt_f32_ubyte0_e32 v65, v65
	v_mul_f32_e32 v72, 0xbed49a78, v72
	v_lshlrev_b32_e32 v185, 16, v23
	v_pk_mul_f32 v[248:249], v[196:197], v[196:197]
	v_add_f32_e32 v132, v246, v132
	v_mov_b32_e32 v97, v8
	v_mov_b32_e32 v8, v67
	v_mul_f32_e32 v65, 0xbed49a78, v65
	v_or_b32_e32 v67, 19, v98
	v_exp_f32_e32 v227, v72
	v_pk_mul_f32 v[242:243], v[184:185], v[184:185]
	v_and_b32_e32 v183, 0xffff0000, v23
	v_add_f32_e32 v132, v248, v132
	v_exp_f32_e32 v176, v65
	v_cvt_f32_ubyte0_e32 v67, v67
	v_lshlrev_b32_e32 v161, 16, v24
	v_lshlrev_b32_e32 v160, 16, v20
	v_pk_mul_f32 v[244:245], v[182:183], v[182:183]
	v_add_f32_e32 v132, v242, v132
	v_mul_f32_e32 v67, 0xbed49a78, v67
	v_pk_mul_f32 v[238:239], v[160:161], v[160:161]
	v_and_b32_e32 v159, 0xffff0000, v24
	v_and_b32_e32 v158, 0xffff0000, v20
	v_add_f32_e32 v132, v244, v132
	v_exp_f32_e32 v232, v67
	v_mul_f32_e32 v26, v102, v35
	v_lshlrev_b32_e32 v102, 16, v21
	v_pk_mul_f32 v[240:241], v[158:159], v[158:159]
	v_mul_f32_e32 v13, 0.15915494, v13
	v_add_f32_e32 v132, v238, v132
	v_mul_f32_e32 v72, v227, v99
	v_mul_f32_e32 v30, v110, v35
	v_pk_mul_f32 v[234:235], v[102:103], v[102:103]
	v_and_b32_e32 v110, 0xffff0000, v21
	v_fract_f32_e32 v13, v13
	v_add_f32_e32 v132, v240, v132
	v_mov_b32_e32 v96, v66
	v_mul_f32_e32 v66, v176, v99
	v_mul_f32_e32 v72, 0.15915494, v72
	v_pk_mul_f32 v[236:237], v[110:111], v[110:111]
	v_sin_f32_e32 v21, v13
	v_cos_f32_e32 v20, v13
	v_mul_f32_e32 v13, v176, v35
	v_lshlrev_b32_e32 v176, 16, v10
	v_add_f32_e32 v132, v234, v132
	v_mul_f32_e32 v56, v166, v99
	v_fract_f32_e32 v72, v72
	v_and_b32_e32 v166, 0xffff0000, v10
	v_pk_mul_f32 v[136:137], v[176:177], v[176:177]
; #define SBAR() __builtin_amdgcn_sched_barrier(0)
; __device__ __forceinline__ void sincos_fast(float ang, float& sn, float& cs) { const float f = __builtin_amdgcn_fractf(ang * 0.15915494309189535f); sn = __builtin_amdgcn_sinf(f); cs = __builtin_amdgcn_cosf(f); }
; template <int MODE, int QMODE> ...
;     ...
;       { auto rr = __builtin_amdgcn_permlane32_swap(__float_as_uint(ssq), __float_as_uint(ssq), false, false); ssq = __uint_as_float(rr[0]) + __uint_as_float(rr[1]); }
;       const float rn = 1.0f / sqrtf(ssq * (1.0f / 128.0f) + 1e-6f);
;       const float posr = (float)(t >> 6), posc = (float)(t & 63);
; #pragma unroll
;       for (int hf = 0; hf < 2; ++hf)
; #pragma unroll
;         for (int dd = 0; dd < 2; ++dd) { const int da = hf * 4 + dd, db = da + 2;
;           const f32x4 ga0 = *(const f32x4*)(qg + da * 16 + hi * 8), ga1 = *(const f32x4*)(qg + da * 16 + hi * 8 + 4), gb0 = *(const f32x4*)(qg + db * 16 + hi * 8), gb1 = *(const f32x4*)(qg + db * 16 + hi * 8 + 4);
;           float ya[8], yb[8];
; #pragma unroll
;           for (int j = 0; j < 8; ++j) { const int i = dd * 16 + hi * 8 + j; const float inv = __builtin_amdgcn_exp2f(-(float)i * (L2T / 32.0f));
;             float sn, cs; sincos_fast((hf ? posc : posr) * inv, sn, cs);
;             const float x1 = bf2f(qr[da][j]) * rn * (j < 4 ? ga0[j & 3] : ga1[j & 3]), x2 = bf2f(qr[db][j]) * rn * (j < 4 ? gb0[j & 3] : gb1[j & 3]);
;             ya[j] = x1 * cs - x2 * sn; yb[j] = x2 * cs + x1 * sn; }
;           u32x4 wa = {cvtpk(ya[0], ya[1]), cvtpk(ya[2], ya[3]), cvtpk(ya[4], ya[5]), cvtpk(ya[6], ya[7])}, wb = {cvtpk(yb[0], yb[1]), cvtpk(yb[2], yb[3]), cvtpk(yb[4], yb[5]), cvtpk(yb[6], yb[7])};
;           qr[da] = *reinterpret_cast<bf16x8*>(&wa); qr[db] = *reinterpret_cast<bf16x8*>(&wb); SBAR(); }
	v_add_f32_e32 v132, v236, v132
	v_mov_b32_e32 v76, v70
	v_mul_f32_e32 v70, v232, v99
	v_sin_f32_e32 v99, v72
	v_cos_f32_e32 v98, v72
	v_mul_f32_e32 v72, v126, v35
	v_lshlrev_b32_e32 v126, 16, v11
	v_pk_mul_f32 v[130:131], v[166:167], v[166:167]
	v_add_f32_e32 v132, v136, v132
	v_and_b32_e32 v24, 0xffff0000, v11
	v_pk_mul_f32 v[192:193], v[126:127], v[126:127]
	v_add_f32_e32 v130, v130, v132
	v_lshlrev_b32_e32 v17, 16, v16
	v_and_b32_e32 v23, 0xffff0000, v16
	v_lshlrev_b32_e32 v16, 16, v12
	v_pk_mul_f32 v[134:135], v[24:25], v[24:25]
	v_add_f32_e32 v130, v192, v130
	v_and_b32_e32 v22, 0xffff0000, v12
	v_pk_mul_f32 v[200:201], v[16:17], v[16:17]
	v_add_f32_e32 v130, v134, v130
	v_pk_mul_f32 v[186:187], v[22:23], v[22:23]
	v_add_f32_e32 v130, v200, v130
	v_add_f32_e32 v130, v186, v130
	v_fmac_f32_e32 v130, v36, v36
	v_fmac_f32_e32 v130, v34, v34
	v_add_f32_e32 v130, v247, v130
	v_add_f32_e32 v130, v249, v130
	v_add_f32_e32 v130, v243, v130
	v_add_f32_e32 v130, v245, v130
	v_add_f32_e32 v130, v239, v130
	v_add_f32_e32 v130, v241, v130
	v_add_f32_e32 v130, v235, v130
	v_add_f32_e32 v130, v237, v130
	v_add_f32_e32 v130, v137, v130
	v_add_f32_e32 v130, v131, v130
	v_add_f32_e32 v130, v193, v130
	v_add_f32_e32 v130, v135, v130
	v_add_f32_e32 v130, v201, v130
	v_pk_mul_f32 v[84:85], v[38:39], v[38:39]
	v_add_f32_e32 v130, v187, v130
	v_add_f32_e32 v84, v84, v130
	v_add_f32_e32 v84, v85, v84
	v_mov_b32_e32 v85, v84
	s_nop 1
	v_permlane32_swap_b32_e32 v84, v85
	v_add_f32_e32 v84, v84, v85
	v_fmamk_f32 v84, v84, 0x3c000000, v1
	v_mul_f32_e32 v85, 0x4f800000, v84
	v_cmp_gt_f32_e32 vcc, s57, v84
	v_mul_f32_e32 v130, v251, v35
	v_mul_f32_e32 v130, 0.15915494, v130
	v_cndmask_b32_e32 v84, v84, v85, vcc
	v_sqrt_f32_e32 v85, v84
	v_mov_b32_e32 v114, v43
	v_mov_b32_e32 v115, v42
	v_mov_b32_e32 v112, v51
	v_add_u32_e32 v131, -1, v85
	v_fma_f32 v132, -v131, v85, v84
	v_cmp_ge_f32_e64 s[2:3], 0, v132
	v_add_u32_e32 v132, 1, v85
	v_mov_b32_e32 v113, v50
	v_cndmask_b32_e64 v131, v85, v131, s[2:3]
	v_fma_f32 v85, -v132, v85, v84
	v_cmp_lt_f32_e64 s[2:3], 0, v85
	v_mul_f32_e32 v56, 0.15915494, v56
	v_mul_f32_e32 v64, 0.15915494, v64
	v_cndmask_b32_e64 v85, v131, v132, s[2:3]
	v_mul_f32_e32 v131, 0x37800000, v85
	v_cndmask_b32_e32 v85, v85, v131, vcc
	v_cmp_class_f32_e32 vcc, v84, v224
	v_mul_f32_e32 v28, 0.15915494, v28
	v_mul_f32_e32 v30, 0.15915494, v30
	v_cndmask_b32_e32 v131, v85, v84, vcc
	v_div_scale_f32 v132, s[2:3], v131, v131, 1.0
	v_rcp_f32_e32 v133, v132
	v_fract_f32_e32 v84, v130
	v_mul_f32_e32 v32, 0.15915494, v32
	v_mul_f32_e32 v72, 0.15915494, v72
	v_fma_f32 v130, -v132, v133, 1.0
	v_fmac_f32_e32 v133, v130, v133
	v_div_scale_f32 v130, vcc, 1.0, v131, 1.0
	v_mul_f32_e32 v134, v130, v133
	v_fma_f32 v135, -v132, v134, v130
	v_fmac_f32_e32 v134, v135, v133
	v_fma_f32 v130, -v132, v134, v130
	v_div_fmas_f32 v130, v130, v133, v134
	v_div_fixup_f32 v186, v130, v131, 1.0
	v_pk_mul_f32 v[100:101], v[186:187], v[100:101] op_sel_hi:[0,1]
	v_pk_mul_f32 v[100:101], v[108:109], v[100:101]
	v_fract_f32_e32 v57, v56
	v_pk_mul_f32 v[52:53], v[52:53], v[100:101]
	v_pk_mul_f32 v[108:109], v[124:125], v[100:101]
	v_add_f32_e32 v100, v52, v53
	v_pk_mul_f32 v[52:53], v[186:187], v[106:107] op_sel_hi:[0,1]
	v_pk_mul_f32 v[6:7], v[6:7], v[52:53]
	v_fract_f32_e32 v64, v64
	v_pk_mul_f32 v[48:49], v[48:49], v[6:7]
	v_pk_mul_f32 v[6:7], v[122:123], v[6:7]
	v_sub_f32_e32 v52, v48, v49
	v_add_f32_e32 v53, v6, v7
	v_pk_mul_f32 v[6:7], v[186:187], v[92:93] op_sel_hi:[0,1]
	v_pk_mul_f32 v[6:7], v[96:97], v[6:7]
	v_mul_f32_e32 v66, 0.15915494, v66
	v_pk_mul_f32 v[48:49], v[120:121], v[6:7]
	v_pk_mul_f32 v[6:7], v[44:45], v[6:7]
	v_mul_f32_e32 v70, 0.15915494, v70
	v_add_f32_e32 v44, v6, v7
	v_pk_mul_f32 v[6:7], v[186:187], v[94:95] op_sel_hi:[0,1]
	v_pk_mul_f32 v[6:7], v[8:9], v[6:7]
	v_mul_f32_e32 v26, 0.15915494, v26
	v_pk_mul_f32 v[8:9], v[40:41], v[6:7]
	v_pk_mul_f32 v[6:7], v[116:117], v[6:7]
	v_sub_f32_e32 v40, v8, v9
	v_add_f32_e32 v41, v6, v7
	v_pk_mul_f32 v[6:7], v[186:187], v[68:69] op_sel_hi:[0,1]
	v_pk_mul_f32 v[6:7], v[76:77], v[6:7]
	v_fract_f32_e32 v28, v28
	v_pk_mul_f32 v[8:9], v[114:115], v[6:7]
	v_pk_mul_f32 v[6:7], v[42:43], v[6:7]
	v_sub_f32_e32 v8, v8, v9
	v_add_f32_e32 v9, v6, v7
	v_pk_mul_f32 v[6:7], v[186:187], v[74:75] op_sel_hi:[0,1]
	v_pk_mul_f32 v[2:3], v[2:3], v[6:7]
	v_fract_f32_e32 v31, v30
	v_pk_mul_f32 v[6:7], v[50:51], v[2:3]
	v_pk_mul_f32 v[2:3], v[112:113], v[2:3]
	v_fract_f32_e32 v32, v32
	v_fract_f32_e32 v73, v72
	v_add_f32_e32 v43, v2, v3
	v_pk_mul_f32 v[2:3], v[186:187], v[54:55] op_sel_hi:[0,1]
	v_mov_b32_e32 v104, v47
	v_mov_b32_e32 v105, v46
	v_sin_f32_e32 v56, v57
	v_cos_f32_e32 v57, v57
	v_sin_f32_e32 v65, v64
	v_cos_f32_e32 v64, v64
	v_fract_f32_e32 v67, v66
	v_fract_f32_e32 v70, v70
	v_fract_f32_e32 v27, v26
	v_sin_f32_e32 v29, v28
	v_cos_f32_e32 v28, v28
	v_sin_f32_e32 v30, v31
	v_cos_f32_e32 v31, v31
	v_sin_f32_e32 v33, v32
	v_cos_f32_e32 v32, v32
	v_sin_f32_e32 v72, v73
	v_cos_f32_e32 v73, v73
	v_pk_mul_f32 v[2:3], v[60:61], v[2:3]
	v_sin_f32_e32 v66, v67
	v_cos_f32_e32 v67, v67
	v_sin_f32_e32 v71, v70
	v_cos_f32_e32 v70, v70
	v_sin_f32_e32 v26, v27
	v_cos_f32_e32 v27, v27
	v_sub_f32_e32 v42, v6, v7
	v_pk_mul_f32 v[6:7], v[104:105], v[2:3]
	v_pk_mul_f32 v[2:3], v[46:47], v[2:3]
	v_mul_f32_e32 v12, v232, v35
	v_sub_f32_e32 v6, v6, v7
	v_add_f32_e32 v7, v2, v3
	v_pk_mul_f32 v[2:3], v[186:187], v[62:63] op_sel_hi:[0,1]
	v_mov_b32_e32 v118, v59
	v_mov_b32_e32 v119, v58
	v_mul_f32_e32 v13, 0.15915494, v13
	v_mul_f32_e32 v12, 0.15915494, v12
	v_pk_mul_f32 v[2:3], v[4:5], v[2:3]
	v_mov_b32_e32 v142, v57
	v_mov_b32_e32 v143, v56
; #define SBAR() __builtin_amdgcn_sched_barrier(0)
; __device__ __forceinline__ void sincos_fast(float ang, float& sn, float& cs) { const float f = __builtin_amdgcn_fractf(ang * 0.15915494309189535f); sn = __builtin_amdgcn_sinf(f); cs = __builtin_amdgcn_cosf(f); }
; template <int MODE, int QMODE> ...
;     ...
;         for (int dd = 0; dd < 2; ++dd) { const int da = hf * 4 + dd, db = da + 2;
;           const f32x4 ga0 = *(const f32x4*)(qg + da * 16 + hi * 8), ga1 = *(const f32x4*)(qg + da * 16 + hi * 8 + 4), gb0 = *(const f32x4*)(qg + db * 16 + hi * 8), gb1 = *(const f32x4*)(qg + db * 16 + hi * 8 + 4);
;           float ya[8], yb[8];
; #pragma unroll
;           for (int j = 0; j < 8; ++j) { const int i = dd * 16 + hi * 8 + j; const float inv = __builtin_amdgcn_exp2f(-(float)i * (L2T / 32.0f));
;             float sn, cs; sincos_fast((hf ? posc : posr) * inv, sn, cs);
;             const float x1 = bf2f(qr[da][j]) * rn * (j < 4 ? ga0[j & 3] : ga1[j & 3]), x2 = bf2f(qr[db][j]) * rn * (j < 4 ? gb0[j & 3] : gb1[j & 3]);
;             ya[j] = x1 * cs - x2 * sn; yb[j] = x2 * cs + x1 * sn; }
;           u32x4 wa = {cvtpk(ya[0], ya[1]), cvtpk(ya[2], ya[3]), cvtpk(ya[4], ya[5]), cvtpk(ya[6], ya[7])}, wb = {cvtpk(yb[0], yb[1]), cvtpk(yb[2], yb[3]), cvtpk(yb[4], yb[5]), cvtpk(yb[6], yb[7])};
;           qr[da] = *reinterpret_cast<bf16x8*>(&wa); qr[db] = *reinterpret_cast<bf16x8*>(&wb); SBAR(); }
	v_mov_b32_e32 v144, v65
	v_mov_b32_e32 v145, v64
	v_mov_b32_e32 v146, v29
	v_mov_b32_e32 v147, v28
	v_mov_b32_e32 v148, v31
	v_mov_b32_e32 v149, v30
	v_mov_b32_e32 v150, v33
	v_mov_b32_e32 v151, v32
	v_mov_b32_e32 v152, v73
	v_mov_b32_e32 v153, v72
	v_mov_b32_e32 v154, v79
	v_mov_b32_e32 v155, v78
	v_mov_b32_e32 v156, v81
	v_mov_b32_e32 v157, v80
	v_fract_f32_e32 v13, v13
	v_fract_f32_e32 v12, v12
	v_pk_mul_f32 v[4:5], v[58:59], v[2:3]
	v_pk_mul_f32 v[2:3], v[118:119], v[2:3]
	v_mov_b32_e32 v162, v67
	v_mov_b32_e32 v163, v66
	v_mov_b32_e32 v164, v71
	v_mov_b32_e32 v165, v70
	v_mov_b32_e32 v168, v83
	v_mov_b32_e32 v169, v82
	v_mov_b32_e32 v170, v89
	v_mov_b32_e32 v171, v88
	v_mov_b32_e32 v174, v91
	v_mov_b32_e32 v175, v90
	v_mov_b32_e32 v172, v99
	v_mov_b32_e32 v173, v98
	v_mov_b32_e32 v128, v27
	v_mov_b32_e32 v129, v26
	v_mov_b32_e32 v194, v87
	v_mov_b32_e32 v195, v86
	v_sin_f32_e32 v10, v13
	v_cos_f32_e32 v11, v13
	v_sin_f32_e32 v13, v12
	v_cos_f32_e32 v12, v12
	v_sin_f32_e32 v14, v15
	v_cos_f32_e32 v15, v15
	v_sin_f32_e32 v85, v84
	v_cos_f32_e32 v84, v84
	v_sub_f32_e32 v108, v108, v109
	v_sub_f32_e32 v48, v48, v49
	v_sub_f32_e32 v4, v4, v5
	v_add_f32_e32 v2, v2, v3
	v_cvt_pk_bf16_f32 v134, v108, v52
	v_cvt_pk_bf16_f32 v135, v48, v40
	v_cvt_pk_bf16_f32 v136, v8, v42
	v_cvt_pk_bf16_f32 v137, v6, v4
	v_cvt_pk_bf16_f32 v130, v100, v53
	v_cvt_pk_bf16_f32 v131, v44, v41
	v_cvt_pk_bf16_f32 v132, v9, v43
	v_cvt_pk_bf16_f32 v133, v7, v2
	global_load_dwordx4 v[2:5], v37, s[54:55] offset:64
	global_load_dwordx4 v[6:9], v37, s[54:55] offset:192
	global_load_dwordx4 v[40:43], v37, s[54:55] offset:80
	global_load_dwordx4 v[44:47], v37, s[54:55] offset:208
	v_pk_mul_f32 v[48:49], v[186:187], v[206:207] op_sel_hi:[0,1]
	v_pk_mul_f32 v[50:51], v[186:187], v[204:205] op_sel_hi:[0,1]
	v_pk_mul_f32 v[52:53], v[186:187], v[190:191] op_sel_hi:[0,1]
	v_pk_mul_f32 v[54:55], v[186:187], v[188:189] op_sel_hi:[0,1]
	v_pk_mul_f32 v[58:59], v[186:187], v[180:181] op_sel_hi:[0,1]
	v_pk_mul_f32 v[60:61], v[186:187], v[178:179] op_sel_hi:[0,1]
	v_pk_mul_f32 v[62:63], v[186:187], v[140:141] op_sel_hi:[0,1]
	v_pk_mul_f32 v[68:69], v[186:187], v[138:139] op_sel_hi:[0,1]
	s_waitcnt vmcnt(3)
	v_mov_b32_e32 v74, v2
	s_waitcnt vmcnt(2)
	v_mov_b32_e32 v75, v6
	v_mov_b32_e32 v6, v3
	v_mov_b32_e32 v2, v4
	v_mov_b32_e32 v3, v8
	v_mov_b32_e32 v8, v5
	s_waitcnt vmcnt(1)
	v_mov_b32_e32 v4, v40
	s_waitcnt vmcnt(0)
	v_mov_b32_e32 v5, v44
	v_mov_b32_e32 v44, v41
	v_mov_b32_e32 v40, v42
	v_mov_b32_e32 v41, v46
	v_mov_b32_e32 v46, v43
	v_pk_mul_f32 v[42:43], v[48:49], v[74:75]
	v_pk_mul_f32 v[6:7], v[50:51], v[6:7]
	v_pk_mul_f32 v[2:3], v[52:53], v[2:3]
	v_pk_mul_f32 v[8:9], v[54:55], v[8:9]
	v_pk_mul_f32 v[4:5], v[58:59], v[4:5]
	v_pk_mul_f32 v[44:45], v[60:61], v[44:45]
	v_pk_mul_f32 v[40:41], v[62:63], v[40:41]
	v_pk_mul_f32 v[46:47], v[68:69], v[46:47]
	v_pk_mul_f32 v[48:49], v[142:143], v[42:43]
	v_pk_mul_f32 v[42:43], v[56:57], v[42:43]
	v_pk_mul_f32 v[50:51], v[64:65], v[6:7]
	v_pk_mul_f32 v[6:7], v[144:145], v[6:7]
	v_pk_mul_f32 v[52:53], v[162:163], v[2:3]
	v_pk_mul_f32 v[2:3], v[66:67], v[2:3]
	v_pk_mul_f32 v[54:55], v[70:71], v[8:9]
	v_pk_mul_f32 v[8:9], v[164:165], v[8:9]
	v_pk_mul_f32 v[56:57], v[168:169], v[4:5]
	v_pk_mul_f32 v[4:5], v[82:83], v[4:5]
	v_pk_mul_f32 v[58:59], v[88:89], v[44:45]
	v_pk_mul_f32 v[44:45], v[170:171], v[44:45]
	v_pk_mul_f32 v[60:61], v[174:175], v[40:41]
	v_pk_mul_f32 v[40:41], v[90:91], v[40:41]
	v_pk_mul_f32 v[62:63], v[98:99], v[46:47]
	v_pk_mul_f32 v[46:47], v[172:173], v[46:47]
	v_sub_f32_e32 v48, v48, v49
	v_add_f32_e32 v42, v42, v43
	v_sub_f32_e32 v43, v50, v51
	v_add_f32_e32 v6, v6, v7
	v_sub_f32_e32 v7, v52, v53
	v_add_f32_e32 v2, v2, v3
	v_sub_f32_e32 v3, v54, v55
	v_add_f32_e32 v8, v8, v9
	v_sub_f32_e32 v9, v56, v57
	v_add_f32_e32 v4, v4, v5
	v_sub_f32_e32 v5, v58, v59
	v_add_f32_e32 v44, v44, v45
	v_sub_f32_e32 v45, v60, v61
	v_add_f32_e32 v40, v40, v41
	v_sub_f32_e32 v41, v62, v63
	v_add_f32_e32 v46, v46, v47
	v_cvt_pk_bf16_f32 v142, v48, v43
	v_cvt_pk_bf16_f32 v143, v7, v3
	v_cvt_pk_bf16_f32 v144, v9, v5
	v_cvt_pk_bf16_f32 v145, v45, v41
	v_cvt_pk_bf16_f32 v138, v42, v6
	v_cvt_pk_bf16_f32 v139, v2, v8
	v_cvt_pk_bf16_f32 v140, v4, v44
	v_cvt_pk_bf16_f32 v141, v40, v46
	global_load_dwordx4 v[2:5], v37, s[54:55] offset:256
	global_load_dwordx4 v[6:9], v37, s[54:55] offset:384
	global_load_dwordx4 v[40:43], v37, s[54:55] offset:272
	global_load_dwordx4 v[44:47], v37, s[54:55] offset:400
	v_pk_mul_f32 v[48:49], v[186:187], v[198:199] op_sel_hi:[0,1]
	v_pk_mul_f32 v[50:51], v[186:187], v[196:197] op_sel_hi:[0,1]
	v_pk_mul_f32 v[52:53], v[186:187], v[184:185] op_sel_hi:[0,1]
	v_pk_mul_f32 v[54:55], v[186:187], v[182:183] op_sel_hi:[0,1]
	v_pk_mul_f32 v[56:57], v[186:187], v[160:161] op_sel_hi:[0,1]
	v_pk_mul_f32 v[58:59], v[186:187], v[158:159] op_sel_hi:[0,1]
	v_pk_mul_f32 v[60:61], v[186:187], v[102:103] op_sel_hi:[0,1]
	v_pk_mul_f32 v[62:63], v[186:187], v[110:111] op_sel_hi:[0,1]
	s_waitcnt vmcnt(3)
	v_mov_b32_e32 v64, v2
	s_waitcnt vmcnt(2)
	v_mov_b32_e32 v65, v6
	v_mov_b32_e32 v6, v3
	v_mov_b32_e32 v2, v4
	v_mov_b32_e32 v3, v8
	v_mov_b32_e32 v8, v5
	s_waitcnt vmcnt(1)
	v_mov_b32_e32 v4, v40
	s_waitcnt vmcnt(0)
; #define SBAR() __builtin_amdgcn_sched_barrier(0)
; __device__ __forceinline__ void sincos_fast(float ang, float& sn, float& cs) { const float f = __builtin_amdgcn_fractf(ang * 0.15915494309189535f); sn = __builtin_amdgcn_sinf(f); cs = __builtin_amdgcn_cosf(f); }
; template <int MODE, int QMODE> ...
;     ...
;         for (int dd = 0; dd < 2; ++dd) { const int da = hf * 4 + dd, db = da + 2;
;           const f32x4 ga0 = *(const f32x4*)(qg + da * 16 + hi * 8), ga1 = *(const f32x4*)(qg + da * 16 + hi * 8 + 4), gb0 = *(const f32x4*)(qg + db * 16 + hi * 8), gb1 = *(const f32x4*)(qg + db * 16 + hi * 8 + 4);
;           float ya[8], yb[8];
; #pragma unroll
;           for (int j = 0; j < 8; ++j) { const int i = dd * 16 + hi * 8 + j; const float inv = __builtin_amdgcn_exp2f(-(float)i * (L2T / 32.0f));
;             float sn, cs; sincos_fast((hf ? posc : posr) * inv, sn, cs);
;             const float x1 = bf2f(qr[da][j]) * rn * (j < 4 ? ga0[j & 3] : ga1[j & 3]), x2 = bf2f(qr[db][j]) * rn * (j < 4 ? gb0[j & 3] : gb1[j & 3]);
;             ya[j] = x1 * cs - x2 * sn; yb[j] = x2 * cs + x1 * sn; }
;           u32x4 wa = {cvtpk(ya[0], ya[1]), cvtpk(ya[2], ya[3]), cvtpk(ya[4], ya[5]), cvtpk(ya[6], ya[7])}, wb = {cvtpk(yb[0], yb[1]), cvtpk(yb[2], yb[3]), cvtpk(yb[4], yb[5]), cvtpk(yb[6], yb[7])};
;           qr[da] = *reinterpret_cast<bf16x8*>(&wa); qr[db] = *reinterpret_cast<bf16x8*>(&wb); SBAR(); }
;     ...
;   if (wid >= 4) __builtin_amdgcn_s_setprio(1);
	v_mov_b32_e32 v5, v44
	v_mov_b32_e32 v44, v41
	v_mov_b32_e32 v40, v42
	v_mov_b32_e32 v41, v46
	v_mov_b32_e32 v46, v43
	v_pk_mul_f32 v[42:43], v[48:49], v[64:65]
	v_pk_mul_f32 v[6:7], v[50:51], v[6:7]
	v_pk_mul_f32 v[2:3], v[52:53], v[2:3]
	v_pk_mul_f32 v[8:9], v[54:55], v[8:9]
	v_pk_mul_f32 v[4:5], v[56:57], v[4:5]
	v_pk_mul_f32 v[44:45], v[58:59], v[44:45]
	v_pk_mul_f32 v[40:41], v[60:61], v[40:41]
	v_pk_mul_f32 v[46:47], v[62:63], v[46:47]
	v_pk_mul_f32 v[48:49], v[128:129], v[42:43]
	v_pk_mul_f32 v[26:27], v[26:27], v[42:43]
	v_pk_mul_f32 v[28:29], v[28:29], v[6:7]
	v_pk_mul_f32 v[6:7], v[146:147], v[6:7]
	v_pk_mul_f32 v[42:43], v[148:149], v[2:3]
	v_pk_mul_f32 v[2:3], v[30:31], v[2:3]
	v_pk_mul_f32 v[30:31], v[32:33], v[8:9]
	v_pk_mul_f32 v[8:9], v[150:151], v[8:9]
	v_pk_mul_f32 v[32:33], v[152:153], v[4:5]
	v_pk_mul_f32 v[4:5], v[72:73], v[4:5]
	v_pk_mul_f32 v[50:51], v[78:79], v[44:45]
	v_pk_mul_f32 v[44:45], v[154:155], v[44:45]
	v_pk_mul_f32 v[52:53], v[156:157], v[40:41]
	v_pk_mul_f32 v[40:41], v[80:81], v[40:41]
	v_pk_mul_f32 v[54:55], v[86:87], v[46:47]
	v_pk_mul_f32 v[46:47], v[194:195], v[46:47]
	v_sub_f32_e32 v48, v48, v49
	v_add_f32_e32 v26, v26, v27
	v_sub_f32_e32 v27, v28, v29
	v_add_f32_e32 v6, v6, v7
	v_sub_f32_e32 v7, v42, v43
	v_add_f32_e32 v2, v2, v3
	v_sub_f32_e32 v3, v30, v31
	v_add_f32_e32 v8, v8, v9
	v_sub_f32_e32 v9, v32, v33
	v_add_f32_e32 v4, v4, v5
	v_sub_f32_e32 v5, v50, v51
	v_add_f32_e32 v28, v44, v45
	v_sub_f32_e32 v29, v52, v53
	v_add_f32_e32 v30, v40, v41
	v_sub_f32_e32 v31, v54, v55
	v_add_f32_e32 v32, v46, v47
	v_cvt_pk_bf16_f32 v150, v48, v27
	v_cvt_pk_bf16_f32 v151, v7, v3
	v_cvt_pk_bf16_f32 v152, v9, v5
	v_cvt_pk_bf16_f32 v153, v29, v31
	v_cvt_pk_bf16_f32 v146, v26, v6
	v_cvt_pk_bf16_f32 v147, v2, v8
	v_cvt_pk_bf16_f32 v148, v4, v28
	v_cvt_pk_bf16_f32 v149, v30, v32
	global_load_dwordx4 v[2:5], v37, s[54:55] offset:320
	global_load_dwordx4 v[6:9], v37, s[54:55] offset:448
	global_load_dwordx4 v[26:29], v37, s[54:55] offset:336
	global_load_dwordx4 v[30:33], v37, s[54:55] offset:464
	v_mul_f32_e32 v58, v228, v35
	v_mov_b32_e32 v37, v38
	v_mul_f32_e32 v38, v227, v35
	v_mov_b32_e32 v35, v39
	v_mul_f32_e32 v39, 0.15915494, v58
	v_mul_f32_e32 v38, 0.15915494, v38
	v_fract_f32_e32 v58, v39
	v_fract_f32_e32 v60, v38
	v_pk_mul_f32 v[40:41], v[186:187], v[176:177] op_sel_hi:[0,1]
	v_pk_mul_f32 v[44:45], v[186:187], v[166:167] op_sel_hi:[0,1]
	v_pk_mul_f32 v[48:49], v[186:187], v[126:127] op_sel_hi:[0,1]
	v_sin_f32_e32 v39, v58
	v_cos_f32_e32 v38, v58
	v_sin_f32_e32 v59, v60
	v_cos_f32_e32 v58, v60
	v_mov_b32_e32 v50, v11
	v_mov_b32_e32 v51, v10
	v_pk_mul_f32 v[24:25], v[186:187], v[24:25] op_sel_hi:[0,1]
	v_pk_mul_f32 v[16:17], v[186:187], v[16:17] op_sel_hi:[0,1]
	v_pk_mul_f32 v[22:23], v[186:187], v[22:23] op_sel_hi:[0,1]
	v_pk_mul_f32 v[36:37], v[186:187], v[36:37] op_sel_hi:[0,1]
	v_mov_b32_e32 v42, v19
	v_mov_b32_e32 v43, v18
	v_mov_b32_e32 v46, v21
	v_mov_b32_e32 v47, v20
	v_mov_b32_e32 v54, v15
	v_mov_b32_e32 v55, v14
	v_pk_mul_f32 v[34:35], v[186:187], v[34:35] op_sel_hi:[0,1]
	v_mov_b32_e32 v52, v13
	v_mov_b32_e32 v53, v12
	v_mov_b32_e32 v56, v85
	v_mov_b32_e32 v57, v84
	v_mov_b32_e32 v60, v39
	v_mov_b32_e32 v61, v38
	s_waitcnt vmcnt(3)
	v_mov_b32_e32 v62, v2
	s_waitcnt vmcnt(2)
	v_mov_b32_e32 v63, v6
	v_mov_b32_e32 v6, v3
	v_mov_b32_e32 v2, v4
	v_mov_b32_e32 v3, v8
	v_mov_b32_e32 v8, v5
	s_waitcnt vmcnt(1)
	v_mov_b32_e32 v4, v26
	s_waitcnt vmcnt(0)
	v_mov_b32_e32 v5, v30
	v_mov_b32_e32 v30, v27
	v_mov_b32_e32 v26, v28
	v_mov_b32_e32 v27, v32
	v_pk_mul_f32 v[40:41], v[40:41], v[62:63]
	v_pk_mul_f32 v[6:7], v[44:45], v[6:7]
	v_pk_mul_f32 v[2:3], v[48:49], v[2:3]
	v_pk_mul_f32 v[8:9], v[24:25], v[8:9]
	v_pk_mul_f32 v[4:5], v[16:17], v[4:5]
	v_pk_mul_f32 v[16:17], v[22:23], v[30:31]
	v_pk_mul_f32 v[22:23], v[36:37], v[26:27]
	v_pk_mul_f32 v[18:19], v[18:19], v[40:41]
	v_pk_mul_f32 v[20:21], v[20:21], v[6:7]
	v_pk_mul_f32 v[26:27], v[50:51], v[2:3]
	v_pk_mul_f32 v[2:3], v[10:11], v[2:3]
	v_mov_b32_e32 v32, v29
	v_pk_mul_f32 v[10:11], v[12:13], v[8:9]
	v_pk_mul_f32 v[12:13], v[54:55], v[4:5]
	v_pk_mul_f32 v[4:5], v[14:15], v[4:5]
	v_add_f32_e32 v18, v18, v19
	v_sub_f32_e32 v19, v20, v21
	v_add_f32_e32 v20, v2, v3
	v_pk_mul_f32 v[2:3], v[34:35], v[32:33]
	v_pk_mul_f32 v[8:9], v[52:53], v[8:9]
	v_pk_mul_f32 v[14:15], v[84:85], v[16:17]
	v_pk_mul_f32 v[16:17], v[56:57], v[16:17]
	v_sub_f32_e32 v10, v10, v11
	v_add_f32_e32 v11, v4, v5
	v_pk_mul_f32 v[4:5], v[58:59], v[2:3]
	v_add_f32_e32 v8, v8, v9
	v_sub_f32_e32 v9, v12, v13
	v_add_f32_e32 v13, v16, v17
	v_sub_f32_e32 v16, v4, v5
	v_mov_b32_e32 v4, v59
	v_mov_b32_e32 v5, v58
	v_pk_mul_f32 v[24:25], v[42:43], v[40:41]
	v_pk_mul_f32 v[6:7], v[46:47], v[6:7]
	v_pk_mul_f32 v[30:31], v[38:39], v[22:23]
	v_pk_mul_f32 v[22:23], v[60:61], v[22:23]
	v_pk_mul_f32 v[2:3], v[4:5], v[2:3]
	v_sub_f32_e32 v24, v24, v25
	v_add_f32_e32 v6, v6, v7
	v_sub_f32_e32 v7, v26, v27
	v_sub_f32_e32 v12, v14, v15
	v_sub_f32_e32 v14, v30, v31
	v_add_f32_e32 v15, v22, v23
	v_add_f32_e32 v2, v2, v3
	v_cvt_pk_bf16_f32 v158, v24, v19
	v_cvt_pk_bf16_f32 v159, v7, v10
	v_cvt_pk_bf16_f32 v160, v9, v12
	v_cvt_pk_bf16_f32 v161, v14, v16
	v_cvt_pk_bf16_f32 v154, v18, v6
	v_cvt_pk_bf16_f32 v155, v20, v8
	v_cvt_pk_bf16_f32 v156, v11, v13
	v_cvt_pk_bf16_f32 v157, v15, v2
	s_nop 0
	s_cmp_lt_i32 s18, 4
	s_cbranch_scc1 .LBB0_170
	s_setprio 3
